# grid barriers: XCD leaders wait on the cross-XCD arrival counter instead of the release generation word (one atomic round trip less on the release path)
# speedup vs baseline: 1.0093x; 1.0060x over previous
; __device__ __forceinline__ unsigned xb_ld(unsigned* p)              { return __hip_atomic_load(p, __ATOMIC_RELAXED, __HIP_MEMORY_SCOPE_AGENT); }
; __device__ __forceinline__ unsigned xb_add(unsigned* p, unsigned v) { return __hip_atomic_fetch_add(p, v, __ATOMIC_RELAXED, __HIP_MEMORY_SCOPE_AGENT); }
; #define XB_SPIN(cond, bar) do { unsigned _sp = 0; while (cond) { __builtin_amdgcn_s_sleep(1); \
;     if ((++_sp & 255u) == 0u) { if (xb_ld(&(bar)[XB_TMO])) break; if (_sp > XB_SPIN_CAP) { atomicAdd(&(bar)[XB_TMO], 1u); break; } } } } while (0)
; __device__ __forceinline__ void xcd_barrier(const XcdBarrier& b) {
;     ...
;             const unsigned og = xb_add(&bar[XB_TOP], 1u);
;             const unsigned tg = og / nx;
;             if (og + 1u == (tg + 1u) * nx) xb_add(&bar[XB_TOPGEN], 1u);
;             else XB_SPIN(xb_ld(&bar[XB_TOPGEN]) == tg, bar);
.LBB0_180:
	s_or_b64 exec, exec, s[10:11]
	v_cvt_f32_u32_e32 v3, v0
	s_waitcnt vmcnt(0)
	v_readfirstlane_b32 s3, v2
	s_add_u32 s10, s22, 0x3500
	s_addc_u32 s11, s23, 0
	s_add_u32 s98, s22, 0x3400
	s_addc_u32 s99, s23, 0
	v_rcp_iflag_f32_e32 v3, v3
	v_add_u32_e32 v1, s3, v1
	v_add_u32_e32 v4, 1, v1
	s_mov_b64 s[12:13], -1
	v_mul_f32_e32 v2, 0x4f7ffffe, v3
	v_cvt_u32_f32_e32 v2, v2
	v_sub_u32_e32 v3, 0, v0
	v_mul_lo_u32 v3, v3, v2
	v_mul_hi_u32 v3, v2, v3
	v_add_u32_e32 v2, v2, v3
	v_mul_hi_u32 v2, v1, v2
	v_mul_lo_u32 v3, v2, v0
	v_sub_u32_e32 v1, v1, v3
	v_add_u32_e32 v5, 1, v2
	v_cmp_ge_u32_e32 vcc, v1, v0
	v_sub_u32_e32 v3, v1, v0
	s_nop 0
	v_cndmask_b32_e32 v2, v2, v5, vcc
	v_cndmask_b32_e32 v1, v1, v3, vcc
	v_add_u32_e32 v3, 1, v2
	v_cmp_ge_u32_e32 vcc, v1, v0
	s_nop 1
	v_cndmask_b32_e32 v2, v2, v3, vcc
	v_mul_lo_u32 v1, v0, v2
	v_add_u32_e32 v0, v1, v0
	v_mov_b32_e32 v250, v0
	v_cmp_ne_u32_e32 vcc, v4, v0
	v_mov_b64_e32 v[0:1], s[10:11]
	s_and_saveexec_b64 s[8:9], vcc
	s_cbranch_execz .LBB0_192
	v_mov_b32_e32 v0, 0
	global_load_dword v1, v0, s[98:99] sc1
	s_mov_b64 s[16:17], 0
	s_waitcnt vmcnt(0)
	v_cmp_lt_u32_e32 vcc, v1, v250
	s_and_saveexec_b64 s[14:15], vcc
	s_cbranch_execz .LBB0_191
	s_add_u32 s12, s22, 0x200
	s_addc_u32 s13, s23, 0
	s_mov_b32 s3, 1
	s_branch .LBB0_184

; __device__ __forceinline__ unsigned xb_ld(unsigned* p)              { return __hip_atomic_load(p, __ATOMIC_RELAXED, __HIP_MEMORY_SCOPE_AGENT); }
; #define XB_SPIN(cond, bar) do { unsigned _sp = 0; while (cond) { __builtin_amdgcn_s_sleep(1); \
;     if ((++_sp & 255u) == 0u) { if (xb_ld(&(bar)[XB_TMO])) break; if (_sp > XB_SPIN_CAP) { atomicAdd(&(bar)[XB_TMO], 1u); break; } } } } while (0)
; __device__ __forceinline__ void xcd_barrier(const XcdBarrier& b) {
;     ...
;             else XB_SPIN(xb_ld(&bar[XB_TOPGEN]) == tg, bar);
.LBB0_188:
	global_load_dword v1, v0, s[98:99] sc1
	s_add_i32 s3, s3, 1
	s_mov_b64 s[30:31], -1
	s_waitcnt vmcnt(0)
	v_cmp_ge_u32_e32 vcc, v1, v250
	s_orn2_b64 s[36:37], vcc, exec
	s_branch .LBB0_183

; __device__ __forceinline__ unsigned xb_ld(unsigned* p)              { return __hip_atomic_load(p, __ATOMIC_RELAXED, __HIP_MEMORY_SCOPE_AGENT); }
; #define XB_SPIN(cond, bar) do { unsigned _sp = 0; while (cond) { __builtin_amdgcn_s_sleep(1); \
;     if ((++_sp & 255u) == 0u) { if (xb_ld(&(bar)[XB_TMO])) break; if (_sp > XB_SPIN_CAP) { atomicAdd(&(bar)[XB_TMO], 1u); break; } } } } while (0)
; __device__ __forceinline__ void xcd_barrier(const XcdBarrier& b) {
;     ...
;             else XB_SPIN(xb_ld(&bar[XB_TOPGEN]) == tg, bar);
.LBB0_1443:
	global_load_dword v1, v0, s[98:99] sc1
	s_add_i32 s3, s3, 1
	s_mov_b64 s[28:29], -1
	s_waitcnt vmcnt(0)
	v_cmp_ge_u32_e32 vcc, v1, v250
	s_orn2_b64 s[34:35], vcc, exec
	s_branch .LBB0_1438

; __device__ __forceinline__ unsigned xb_ld(unsigned* p)              { return __hip_atomic_load(p, __ATOMIC_RELAXED, __HIP_MEMORY_SCOPE_AGENT); }
; #define XB_SPIN(cond, bar) do { unsigned _sp = 0; while (cond) { __builtin_amdgcn_s_sleep(1); \
;     if ((++_sp & 255u) == 0u) { if (xb_ld(&(bar)[XB_TMO])) break; if (_sp > XB_SPIN_CAP) { atomicAdd(&(bar)[XB_TMO], 1u); break; } } } } while (0)
; __device__ __forceinline__ void xcd_barrier(const XcdBarrier& b) {
;     ...
;             else XB_SPIN(xb_ld(&bar[XB_TOPGEN]) == tg, bar);
.LBB0_1518:
	global_load_dword v1, v0, s[98:99] sc1
	s_add_i32 s3, s3, 1
	s_mov_b64 s[24:25], -1
	s_waitcnt vmcnt(0)
	v_cmp_ge_u32_e32 vcc, v1, v250
	s_orn2_b64 s[28:29], vcc, exec
	s_branch .LBB0_1513
